# code placement: .p2align 6 before the seven GEMM K-loop head labels (v24 + alignment only)
# speedup vs baseline: 1.0090x; 1.0090x over previous
; template <class Epi, class Sched, bool ALIGN_EPI, bool SP2, int KC>
; __device__ __forceinline__ void gemm_phase(PG8_LAS unsigned char* lds, const Gemm g, const Sched& S, const Epi& E, const int tid) {
;     ...
;         const bool has_next = S.next(ui + 1, nxt);
;         const char* nA = has_next ? (const char*)g.A + (size_t)nxt.pm * tstep : cA; const char* nB = has_next ? (const char*)g.Bt + (size_t)nxt.pn * tstep : cB;
;         for (int t = 0; t < nt; t += 2) {
;             const bool last = (t == nt - 2);
;             const char* a1 = cA + (size_t)(t + 1) * kstep;
;             const char* a2 = last ? nA : cA + (size_t)(t + 2) * kstep; const char* b2 = last ? nB : cB + (size_t)(t + 2) * kstep;
;             const char* a3 = a2 + kstep; const char* b3 = b2 + kstep;
;     ...
;         for (int a = 0; a < 2; ++a)
; #pragma unroll
;             for (int b = 0; b < 2; ++b)
; #pragma unroll
;                 for (int m = 0; m < 4; ++m)
; #pragma unroll
;                     for (int n = 0; n < 2; ++n) acc[a][b][m][n] = (f32x4){0.f, 0.f, 0.f, 0.f};
.LBB0_43:
	s_ashr_i32 s17, s16, 31
	s_lshl_b64 s[18:19], s[16:17], 19
	v_readlane_b32 s15, v252, 15
	s_add_u32 s18, s15, s18
	v_readlane_b32 s15, v252, 16
	s_addc_u32 s19, s15, s19
	s_and_b64 s[20:21], s[12:13], exec
	s_cselect_b32 s17, s19, s23
	s_cselect_b32 s38, s18, s22
	s_ashr_i32 s15, s14, 31
	s_lshl_b64 s[20:21], s[14:15], 19
	s_add_u32 s20, s82, s20
	s_addc_u32 s21, s83, s21
	s_and_b64 s[26:27], s[12:13], exec
	s_cselect_b32 s15, s21, s25
	s_cselect_b32 s39, s20, s24
	s_add_u32 s22, s22, 0x40080
	s_addc_u32 s23, s23, 0
	s_add_u32 s40, s24, 0x100
	v_mov_b32_e32 v0, 0
	s_addc_u32 s41, s25, 0
	s_mov_b32 s42, -2
	v_mov_b32_e32 v1, v0
	v_mov_b32_e32 v2, v0
	v_mov_b32_e32 v3, v0
	v_mov_b32_e32 v4, v0
	v_mov_b32_e32 v5, v0
	v_mov_b32_e32 v6, v0
	v_mov_b32_e32 v7, v0
	v_mov_b32_e32 v8, v0
	v_mov_b32_e32 v9, v0
	v_mov_b32_e32 v10, v0
	v_mov_b32_e32 v11, v0
	v_mov_b32_e32 v16, v0
	v_mov_b32_e32 v17, v0
	v_mov_b32_e32 v18, v0
	v_mov_b32_e32 v19, v0
	v_mov_b32_e32 v24, v0
	v_mov_b32_e32 v25, v0
	v_mov_b32_e32 v26, v0
	v_mov_b32_e32 v27, v0
	v_mov_b32_e32 v32, v0
	v_mov_b32_e32 v33, v0
	v_mov_b32_e32 v34, v0
	v_mov_b32_e32 v35, v0
	v_mov_b32_e32 v40, v0
	v_mov_b32_e32 v41, v0
	v_mov_b32_e32 v42, v0
	v_mov_b32_e32 v43, v0
	v_mov_b32_e32 v48, v0
	v_mov_b32_e32 v49, v0
	v_mov_b32_e32 v50, v0
	v_mov_b32_e32 v51, v0
	v_mov_b32_e32 v12, v0
	v_mov_b32_e32 v13, v0
	v_mov_b32_e32 v14, v0
	v_mov_b32_e32 v15, v0
	v_mov_b32_e32 v20, v0
	v_mov_b32_e32 v21, v0
	v_mov_b32_e32 v22, v0
	v_mov_b32_e32 v23, v0
	v_mov_b32_e32 v28, v0
	v_mov_b32_e32 v29, v0
	v_mov_b32_e32 v30, v0
	v_mov_b32_e32 v31, v0
	v_mov_b32_e32 v36, v0
	v_mov_b32_e32 v37, v0
	v_mov_b32_e32 v38, v0
	v_mov_b32_e32 v39, v0
	v_mov_b32_e32 v44, v0
	v_mov_b32_e32 v45, v0
	v_mov_b32_e32 v46, v0
	v_mov_b32_e32 v47, v0
	v_mov_b32_e32 v52, v0
	v_mov_b32_e32 v53, v0
	v_mov_b32_e32 v54, v0
	v_mov_b32_e32 v55, v0
	v_mov_b32_e32 v56, v0
	v_mov_b32_e32 v57, v0
	v_mov_b32_e32 v58, v0
	v_mov_b32_e32 v59, v0
	v_mov_b32_e32 v60, v0
	v_mov_b32_e32 v61, v0
	v_mov_b32_e32 v62, v0
	v_mov_b32_e32 v63, v0
	v_mov_b32_e32 v64, v0
	v_mov_b32_e32 v65, v0
	v_mov_b32_e32 v66, v0
	v_mov_b32_e32 v67, v0
	v_mov_b32_e32 v68, v0
	v_mov_b32_e32 v69, v0
	v_mov_b32_e32 v70, v0
	v_mov_b32_e32 v71, v0
	v_mov_b32_e32 v76, v0
	v_mov_b32_e32 v77, v0
	v_mov_b32_e32 v78, v0
	v_mov_b32_e32 v79, v0
	v_mov_b32_e32 v84, v0
	v_mov_b32_e32 v85, v0
	v_mov_b32_e32 v86, v0
	v_mov_b32_e32 v87, v0
	v_mov_b32_e32 v88, v0
	v_mov_b32_e32 v89, v0
	v_mov_b32_e32 v90, v0
	v_mov_b32_e32 v91, v0
	v_mov_b32_e32 v96, v0
	v_mov_b32_e32 v97, v0
	v_mov_b32_e32 v98, v0
	v_mov_b32_e32 v99, v0
	v_mov_b32_e32 v104, v0
	v_mov_b32_e32 v105, v0
	v_mov_b32_e32 v106, v0
	v_mov_b32_e32 v107, v0
	v_mov_b32_e32 v112, v0
	v_mov_b32_e32 v113, v0
	v_mov_b32_e32 v114, v0
	v_mov_b32_e32 v115, v0
	v_mov_b32_e32 v72, v0
	v_mov_b32_e32 v73, v0
	v_mov_b32_e32 v74, v0
	v_mov_b32_e32 v75, v0
	v_mov_b32_e32 v80, v0
	v_mov_b32_e32 v81, v0
	v_mov_b32_e32 v82, v0
	v_mov_b32_e32 v83, v0
	v_mov_b32_e32 v92, v0
	v_mov_b32_e32 v93, v0
	v_mov_b32_e32 v94, v0
	v_mov_b32_e32 v95, v0
	v_mov_b32_e32 v100, v0
	v_mov_b32_e32 v101, v0
	v_mov_b32_e32 v102, v0
	v_mov_b32_e32 v103, v0
	v_mov_b32_e32 v108, v0
	v_mov_b32_e32 v109, v0
	v_mov_b32_e32 v110, v0
	v_mov_b32_e32 v111, v0
	v_mov_b32_e32 v116, v0
	v_mov_b32_e32 v117, v0
	v_mov_b32_e32 v118, v0
	v_mov_b32_e32 v119, v0
	v_mov_b32_e32 v120, v0
	v_mov_b32_e32 v121, v0
	v_mov_b32_e32 v122, v0
	v_mov_b32_e32 v123, v0
	v_mov_b32_e32 v124, v0
	v_mov_b32_e32 v125, v0
	v_mov_b32_e32 v126, v0
	v_mov_b32_e32 v127, v0
	.p2align	6

; template <class Epi, class Sched, bool ALIGN_EPI, bool SP2, int KC>
; __device__ __forceinline__ void gemm_phase(PG8_LAS unsigned char* lds, const Gemm g, const Sched& S, const Epi& E, const int tid) {
;     ...
;         const bool has_next = S.next(ui + 1, nxt);
;         const char* nA = has_next ? (const char*)g.A + (size_t)nxt.pm * tstep : cA; const char* nB = has_next ? (const char*)g.Bt + (size_t)nxt.pn * tstep : cB;
;         for (int t = 0; t < nt; t += 2) {
;             const bool last = (t == nt - 2);
;             const char* a1 = cA + (size_t)(t + 1) * kstep;
;             const char* a2 = last ? nA : cA + (size_t)(t + 2) * kstep; const char* b2 = last ? nB : cB + (size_t)(t + 2) * kstep;
;             const char* a3 = a2 + kstep; const char* b3 = b2 + kstep;
;     ...
;         for (int a = 0; a < 2; ++a)
; #pragma unroll
;             for (int b = 0; b < 2; ++b)
; #pragma unroll
;                 for (int m = 0; m < 4; ++m)
; #pragma unroll
;                     for (int n = 0; n < 2; ++n) acc[a][b][m][n] = (f32x4){0.f, 0.f, 0.f, 0.f};
.LBB0_65:
	s_ashr_i32 s17, s16, 31
	s_lshl_b64 s[18:19], s[16:17], 19
	v_readlane_b32 s20, v252, 48
	v_readlane_b32 s21, v252, 49
	s_add_u32 s18, s20, s18
	s_addc_u32 s19, s21, s19
	s_and_b64 s[20:21], s[12:13], exec
	s_cselect_b32 s17, s19, s23
	s_cselect_b32 s38, s18, s22
	s_ashr_i32 s15, s14, 31
	s_lshl_b64 s[20:21], s[14:15], 19
	v_readlane_b32 s15, v252, 44
	s_add_u32 s20, s15, s20
	v_readlane_b32 s15, v252, 45
	s_addc_u32 s21, s15, s21
	s_and_b64 s[26:27], s[12:13], exec
	s_cselect_b32 s15, s21, s25
	s_cselect_b32 s39, s20, s24
	s_add_u32 s22, s22, 0x40080
	s_addc_u32 s23, s23, 0
	s_add_u32 s40, s24, 0x100
	v_mov_b32_e32 v0, 0
	s_addc_u32 s41, s25, 0
	s_mov_b32 s42, -2
	v_mov_b32_e32 v1, v0
	v_mov_b32_e32 v2, v0
	v_mov_b32_e32 v3, v0
	v_mov_b32_e32 v4, v0
	v_mov_b32_e32 v5, v0
	v_mov_b32_e32 v6, v0
	v_mov_b32_e32 v7, v0
	v_mov_b32_e32 v8, v0
	v_mov_b32_e32 v9, v0
	v_mov_b32_e32 v10, v0
	v_mov_b32_e32 v11, v0
	v_mov_b32_e32 v16, v0
	v_mov_b32_e32 v17, v0
	v_mov_b32_e32 v18, v0
	v_mov_b32_e32 v19, v0
	v_mov_b32_e32 v24, v0
	v_mov_b32_e32 v25, v0
	v_mov_b32_e32 v26, v0
	v_mov_b32_e32 v27, v0
	v_mov_b32_e32 v32, v0
	v_mov_b32_e32 v33, v0
	v_mov_b32_e32 v34, v0
	v_mov_b32_e32 v35, v0
	v_mov_b32_e32 v40, v0
	v_mov_b32_e32 v41, v0
	v_mov_b32_e32 v42, v0
	v_mov_b32_e32 v43, v0
	v_mov_b32_e32 v48, v0
	v_mov_b32_e32 v49, v0
	v_mov_b32_e32 v50, v0
	v_mov_b32_e32 v51, v0
	v_mov_b32_e32 v12, v0
	v_mov_b32_e32 v13, v0
	v_mov_b32_e32 v14, v0
	v_mov_b32_e32 v15, v0
	v_mov_b32_e32 v20, v0
	v_mov_b32_e32 v21, v0
	v_mov_b32_e32 v22, v0
	v_mov_b32_e32 v23, v0
	v_mov_b32_e32 v28, v0
	v_mov_b32_e32 v29, v0
	v_mov_b32_e32 v30, v0
	v_mov_b32_e32 v31, v0
	v_mov_b32_e32 v36, v0
	v_mov_b32_e32 v37, v0
	v_mov_b32_e32 v38, v0
	v_mov_b32_e32 v39, v0
	v_mov_b32_e32 v44, v0
	v_mov_b32_e32 v45, v0
	v_mov_b32_e32 v46, v0
	v_mov_b32_e32 v47, v0
	v_mov_b32_e32 v52, v0
	v_mov_b32_e32 v53, v0
	v_mov_b32_e32 v54, v0
	v_mov_b32_e32 v55, v0
	v_mov_b32_e32 v56, v0
	v_mov_b32_e32 v57, v0
	v_mov_b32_e32 v58, v0
	v_mov_b32_e32 v59, v0
	v_mov_b32_e32 v60, v0
	v_mov_b32_e32 v61, v0
	v_mov_b32_e32 v62, v0
	v_mov_b32_e32 v63, v0
	v_mov_b32_e32 v64, v0
	v_mov_b32_e32 v65, v0
	v_mov_b32_e32 v66, v0
	v_mov_b32_e32 v67, v0
	v_mov_b32_e32 v68, v0
	v_mov_b32_e32 v69, v0
	v_mov_b32_e32 v70, v0
	v_mov_b32_e32 v71, v0
	v_mov_b32_e32 v76, v0
	v_mov_b32_e32 v77, v0
	v_mov_b32_e32 v78, v0
	v_mov_b32_e32 v79, v0
	v_mov_b32_e32 v84, v0
	v_mov_b32_e32 v85, v0
	v_mov_b32_e32 v86, v0
	v_mov_b32_e32 v87, v0
	v_mov_b32_e32 v88, v0
	v_mov_b32_e32 v89, v0
	v_mov_b32_e32 v90, v0
	v_mov_b32_e32 v91, v0
	v_mov_b32_e32 v96, v0
	v_mov_b32_e32 v97, v0
	v_mov_b32_e32 v98, v0
	v_mov_b32_e32 v99, v0
	v_mov_b32_e32 v104, v0
	v_mov_b32_e32 v105, v0
	v_mov_b32_e32 v106, v0
	v_mov_b32_e32 v107, v0
	v_mov_b32_e32 v112, v0
	v_mov_b32_e32 v113, v0
	v_mov_b32_e32 v114, v0
	v_mov_b32_e32 v115, v0
	v_mov_b32_e32 v72, v0
	v_mov_b32_e32 v73, v0
	v_mov_b32_e32 v74, v0
	v_mov_b32_e32 v75, v0
	v_mov_b32_e32 v80, v0
	v_mov_b32_e32 v81, v0
	v_mov_b32_e32 v82, v0
	v_mov_b32_e32 v83, v0
	v_mov_b32_e32 v92, v0
	v_mov_b32_e32 v93, v0
	v_mov_b32_e32 v94, v0
	v_mov_b32_e32 v95, v0
	v_mov_b32_e32 v100, v0
	v_mov_b32_e32 v101, v0
	v_mov_b32_e32 v102, v0
	v_mov_b32_e32 v103, v0
	v_mov_b32_e32 v108, v0
	v_mov_b32_e32 v109, v0
	v_mov_b32_e32 v110, v0
	v_mov_b32_e32 v111, v0
	v_mov_b32_e32 v116, v0
	v_mov_b32_e32 v117, v0
	v_mov_b32_e32 v118, v0
	v_mov_b32_e32 v119, v0
	v_mov_b32_e32 v120, v0
	v_mov_b32_e32 v121, v0
	v_mov_b32_e32 v122, v0
	v_mov_b32_e32 v123, v0
	v_mov_b32_e32 v124, v0
	v_mov_b32_e32 v125, v0
	v_mov_b32_e32 v126, v0
	v_mov_b32_e32 v127, v0
	.p2align	6

; template <class Epi, class Sched, bool ALIGN_EPI, bool SP2, int KC>
; __device__ __forceinline__ void gemm_phase(PG8_LAS unsigned char* lds, const Gemm g, const Sched& S, const Epi& E, const int tid) {
;     ...
;         const bool has_next = S.next(ui + 1, nxt);
;         const char* nA = has_next ? (const char*)g.A + (size_t)nxt.pm * tstep : cA; const char* nB = has_next ? (const char*)g.Bt + (size_t)nxt.pn * tstep : cB;
;         for (int t = 0; t < nt; t += 2) {
;             const bool last = (t == nt - 2);
;             const char* a1 = cA + (size_t)(t + 1) * kstep;
;             const char* a2 = last ? nA : cA + (size_t)(t + 2) * kstep; const char* b2 = last ? nB : cB + (size_t)(t + 2) * kstep;
;             const char* a3 = a2 + kstep; const char* b3 = b2 + kstep;
;     ...
;         for (int a = 0; a < 2; ++a)
; #pragma unroll
;             for (int b = 0; b < 2; ++b)
; #pragma unroll
;                 for (int m = 0; m < 4; ++m)
; #pragma unroll
;                     for (int n = 0; n < 2; ++n) acc[a][b][m][n] = (f32x4){0.f, 0.f, 0.f, 0.f};
.LBB0_91:
	s_ashr_i32 s19, s18, 31
	s_lshl_b64 s[22:23], s[18:19], 19
	s_add_u32 s22, s68, s22
	s_addc_u32 s23, s69, s23
	s_and_b64 s[24:25], s[8:9], exec
	s_cselect_b32 s19, s23, s5
	s_cselect_b32 s40, s22, s4
	s_ashr_i32 s17, s16, 31
	s_lshl_b64 s[24:25], s[16:17], 19
	v_readlane_b32 s17, v254, 6
	s_add_u32 s24, s17, s24
	v_readlane_b32 s17, v254, 7
	s_addc_u32 s25, s17, s25
	s_and_b64 s[28:29], s[8:9], exec
	s_cselect_b32 s17, s25, s27
	s_cselect_b32 s41, s24, s26
	s_add_u32 s4, s4, 0x40080
	s_addc_u32 s5, s5, 0
	s_add_u32 s42, s26, 0x100
	v_mov_b32_e32 v0, 0
	s_addc_u32 s43, s27, 0
	s_mov_b32 s44, -2
	v_mov_b32_e32 v1, v0
	v_mov_b32_e32 v2, v0
	v_mov_b32_e32 v3, v0
	v_mov_b32_e32 v8, v0
	v_mov_b32_e32 v9, v0
	v_mov_b32_e32 v10, v0
	v_mov_b32_e32 v11, v0
	v_mov_b32_e32 v16, v0
	v_mov_b32_e32 v17, v0
	v_mov_b32_e32 v18, v0
	v_mov_b32_e32 v19, v0
	v_mov_b32_e32 v24, v0
	v_mov_b32_e32 v25, v0
	v_mov_b32_e32 v26, v0
	v_mov_b32_e32 v27, v0
	v_mov_b32_e32 v32, v0
	v_mov_b32_e32 v33, v0
	v_mov_b32_e32 v34, v0
	v_mov_b32_e32 v35, v0
	v_mov_b32_e32 v40, v0
	v_mov_b32_e32 v41, v0
	v_mov_b32_e32 v42, v0
	v_mov_b32_e32 v43, v0
	v_mov_b32_e32 v48, v0
	v_mov_b32_e32 v49, v0
	v_mov_b32_e32 v50, v0
	v_mov_b32_e32 v51, v0
	v_mov_b32_e32 v56, v0
	v_mov_b32_e32 v57, v0
	v_mov_b32_e32 v58, v0
	v_mov_b32_e32 v59, v0
	v_mov_b32_e32 v4, v0
	v_mov_b32_e32 v5, v0
	v_mov_b32_e32 v6, v0
	v_mov_b32_e32 v7, v0
	v_mov_b32_e32 v12, v0
	v_mov_b32_e32 v13, v0
	v_mov_b32_e32 v14, v0
	v_mov_b32_e32 v15, v0
	v_mov_b32_e32 v20, v0
	v_mov_b32_e32 v21, v0
	v_mov_b32_e32 v22, v0
	v_mov_b32_e32 v23, v0
	v_mov_b32_e32 v28, v0
	v_mov_b32_e32 v29, v0
	v_mov_b32_e32 v30, v0
	v_mov_b32_e32 v31, v0
	v_mov_b32_e32 v36, v0
	v_mov_b32_e32 v37, v0
	v_mov_b32_e32 v38, v0
	v_mov_b32_e32 v39, v0
	v_mov_b32_e32 v44, v0
	v_mov_b32_e32 v45, v0
	v_mov_b32_e32 v46, v0
	v_mov_b32_e32 v47, v0
	v_mov_b32_e32 v52, v0
	v_mov_b32_e32 v53, v0
	v_mov_b32_e32 v54, v0
	v_mov_b32_e32 v55, v0
	v_mov_b32_e32 v60, v0
	v_mov_b32_e32 v61, v0
	v_mov_b32_e32 v62, v0
	v_mov_b32_e32 v63, v0
	v_mov_b32_e32 v80, v0
	v_mov_b32_e32 v81, v0
	v_mov_b32_e32 v82, v0
	v_mov_b32_e32 v83, v0
	v_mov_b32_e32 v88, v0
	v_mov_b32_e32 v89, v0
	v_mov_b32_e32 v90, v0
	v_mov_b32_e32 v91, v0
	v_mov_b32_e32 v96, v0
	v_mov_b32_e32 v97, v0
	v_mov_b32_e32 v98, v0
	v_mov_b32_e32 v99, v0
	v_mov_b32_e32 v104, v0
	v_mov_b32_e32 v105, v0
	v_mov_b32_e32 v106, v0
	v_mov_b32_e32 v107, v0
	v_mov_b32_e32 v112, v0
	v_mov_b32_e32 v113, v0
	v_mov_b32_e32 v114, v0
	v_mov_b32_e32 v115, v0
	v_mov_b32_e32 v120, v0
	v_mov_b32_e32 v121, v0
	v_mov_b32_e32 v122, v0
	v_mov_b32_e32 v123, v0
	v_mov_b32_e32 v128, v0
	v_mov_b32_e32 v129, v0
	v_mov_b32_e32 v130, v0
	v_mov_b32_e32 v131, v0
	v_mov_b32_e32 v136, v0
	v_mov_b32_e32 v137, v0
	v_mov_b32_e32 v138, v0
	v_mov_b32_e32 v139, v0
	v_mov_b32_e32 v84, v0
	v_mov_b32_e32 v85, v0
	v_mov_b32_e32 v86, v0
	v_mov_b32_e32 v87, v0
	v_mov_b32_e32 v92, v0
	v_mov_b32_e32 v93, v0
	v_mov_b32_e32 v94, v0
	v_mov_b32_e32 v95, v0
	v_mov_b32_e32 v100, v0
	v_mov_b32_e32 v101, v0
	v_mov_b32_e32 v102, v0
	v_mov_b32_e32 v103, v0
	v_mov_b32_e32 v108, v0
	v_mov_b32_e32 v109, v0
	v_mov_b32_e32 v110, v0
	v_mov_b32_e32 v111, v0
	v_mov_b32_e32 v116, v0
	v_mov_b32_e32 v117, v0
	v_mov_b32_e32 v118, v0
	v_mov_b32_e32 v119, v0
	v_mov_b32_e32 v124, v0
	v_mov_b32_e32 v125, v0
	v_mov_b32_e32 v126, v0
	v_mov_b32_e32 v127, v0
	v_mov_b32_e32 v132, v0
	v_mov_b32_e32 v133, v0
	v_mov_b32_e32 v134, v0
	v_mov_b32_e32 v135, v0
	v_mov_b32_e32 v140, v0
	v_mov_b32_e32 v141, v0
	v_mov_b32_e32 v142, v0
	v_mov_b32_e32 v143, v0
	.p2align	6

; template <class Epi, class Sched, bool ALIGN_EPI, bool SP2, int KC>
; __device__ __forceinline__ void gemm_phase(PG8_LAS unsigned char* lds, const Gemm g, const Sched& S, const Epi& E, const int tid) {
;     ...
;         const bool has_next = S.next(ui + 1, nxt);
;         const char* nA = has_next ? (const char*)g.A + (size_t)nxt.pm * tstep : cA; const char* nB = has_next ? (const char*)g.Bt + (size_t)nxt.pn * tstep : cB;
;         for (int t = 0; t < nt; t += 2) {
;             const bool last = (t == nt - 2);
;             const char* a1 = cA + (size_t)(t + 1) * kstep;
;             const char* a2 = last ? nA : cA + (size_t)(t + 2) * kstep; const char* b2 = last ? nB : cB + (size_t)(t + 2) * kstep;
;             const char* a3 = a2 + kstep; const char* b3 = b2 + kstep;
;     ...
;         for (int a = 0; a < 2; ++a)
; #pragma unroll
;             for (int b = 0; b < 2; ++b)
; #pragma unroll
;                 for (int m = 0; m < 4; ++m)
; #pragma unroll
;                     for (int n = 0; n < 2; ++n) acc[a][b][m][n] = (f32x4){0.f, 0.f, 0.f, 0.f};
.LBB0_115:
	s_ashr_i32 s15, s14, 31
	s_lshl_b64 s[16:17], s[14:15], 19
	s_add_u32 s16, s68, s16
	s_addc_u32 s17, s69, s17
	s_and_b64 s[18:19], s[8:9], exec
	s_cselect_b32 s15, s17, s23
	s_cselect_b32 s38, s16, s22
	s_ashr_i32 s13, s12, 31
	s_lshl_b64 s[18:19], s[12:13], 19
	v_readlane_b32 s13, v254, 42
	s_add_u32 s18, s13, s18
	v_readlane_b32 s13, v254, 43
	s_addc_u32 s19, s13, s19
	s_and_b64 s[26:27], s[8:9], exec
	s_cselect_b32 s13, s19, s25
	s_cselect_b32 s39, s18, s24
	s_add_u32 s22, s22, 0x40080
	s_addc_u32 s23, s23, 0
	s_add_u32 s40, s24, 0x100
	v_mov_b32_e32 v0, 0
	s_addc_u32 s41, s25, 0
	s_mov_b32 s42, -2
	v_mov_b32_e32 v1, v0
	v_mov_b32_e32 v2, v0
	v_mov_b32_e32 v3, v0
	v_mov_b32_e32 v4, v0
	v_mov_b32_e32 v5, v0
	v_mov_b32_e32 v6, v0
	v_mov_b32_e32 v7, v0
	v_mov_b32_e32 v8, v0
	v_mov_b32_e32 v9, v0
	v_mov_b32_e32 v10, v0
	v_mov_b32_e32 v11, v0
	v_mov_b32_e32 v12, v0
	v_mov_b32_e32 v13, v0
	v_mov_b32_e32 v14, v0
	v_mov_b32_e32 v15, v0
	v_mov_b32_e32 v16, v0
	v_mov_b32_e32 v17, v0
	v_mov_b32_e32 v18, v0
	v_mov_b32_e32 v19, v0
	v_mov_b32_e32 v20, v0
	v_mov_b32_e32 v21, v0
	v_mov_b32_e32 v22, v0
	v_mov_b32_e32 v23, v0
	v_mov_b32_e32 v24, v0
	v_mov_b32_e32 v25, v0
	v_mov_b32_e32 v26, v0
	v_mov_b32_e32 v27, v0
	v_mov_b32_e32 v28, v0
	v_mov_b32_e32 v29, v0
	v_mov_b32_e32 v30, v0
	v_mov_b32_e32 v31, v0
	v_mov_b32_e32 v56, v0
	v_mov_b32_e32 v57, v0
	v_mov_b32_e32 v58, v0
	v_mov_b32_e32 v59, v0
	v_mov_b32_e32 v60, v0
	v_mov_b32_e32 v61, v0
	v_mov_b32_e32 v62, v0
	v_mov_b32_e32 v63, v0
	v_mov_b32_e32 v72, v0
	v_mov_b32_e32 v73, v0
	v_mov_b32_e32 v74, v0
	v_mov_b32_e32 v75, v0
	v_mov_b32_e32 v76, v0
	v_mov_b32_e32 v77, v0
	v_mov_b32_e32 v78, v0
	v_mov_b32_e32 v79, v0
	v_mov_b32_e32 v80, v0
	v_mov_b32_e32 v81, v0
	v_mov_b32_e32 v82, v0
	v_mov_b32_e32 v83, v0
	v_mov_b32_e32 v84, v0
	v_mov_b32_e32 v85, v0
	v_mov_b32_e32 v86, v0
	v_mov_b32_e32 v87, v0
	v_mov_b32_e32 v88, v0
	v_mov_b32_e32 v89, v0
	v_mov_b32_e32 v90, v0
	v_mov_b32_e32 v91, v0
	v_mov_b32_e32 v92, v0
	v_mov_b32_e32 v93, v0
	v_mov_b32_e32 v94, v0
	v_mov_b32_e32 v95, v0
	v_mov_b32_e32 v32, v0
	v_mov_b32_e32 v33, v0
	v_mov_b32_e32 v34, v0
	v_mov_b32_e32 v35, v0
	v_mov_b32_e32 v36, v0
	v_mov_b32_e32 v37, v0
	v_mov_b32_e32 v38, v0
	v_mov_b32_e32 v39, v0
	v_mov_b32_e32 v40, v0
	v_mov_b32_e32 v41, v0
	v_mov_b32_e32 v42, v0
	v_mov_b32_e32 v43, v0
	v_mov_b32_e32 v44, v0
	v_mov_b32_e32 v45, v0
	v_mov_b32_e32 v46, v0
	v_mov_b32_e32 v47, v0
	v_mov_b32_e32 v48, v0
	v_mov_b32_e32 v49, v0
	v_mov_b32_e32 v50, v0
	v_mov_b32_e32 v51, v0
	v_mov_b32_e32 v52, v0
	v_mov_b32_e32 v53, v0
	v_mov_b32_e32 v54, v0
	v_mov_b32_e32 v55, v0
	v_mov_b32_e32 v64, v0
	v_mov_b32_e32 v65, v0
	v_mov_b32_e32 v66, v0
	v_mov_b32_e32 v67, v0
	v_mov_b32_e32 v68, v0
	v_mov_b32_e32 v69, v0
	v_mov_b32_e32 v70, v0
	v_mov_b32_e32 v71, v0
	v_mov_b32_e32 v96, v0
	v_mov_b32_e32 v97, v0
	v_mov_b32_e32 v98, v0
	v_mov_b32_e32 v99, v0
	v_mov_b32_e32 v100, v0
	v_mov_b32_e32 v101, v0
	v_mov_b32_e32 v102, v0
	v_mov_b32_e32 v103, v0
	v_mov_b32_e32 v104, v0
	v_mov_b32_e32 v105, v0
	v_mov_b32_e32 v106, v0
	v_mov_b32_e32 v107, v0
	v_mov_b32_e32 v108, v0
	v_mov_b32_e32 v109, v0
	v_mov_b32_e32 v110, v0
	v_mov_b32_e32 v111, v0
	v_mov_b32_e32 v112, v0
	v_mov_b32_e32 v113, v0
	v_mov_b32_e32 v114, v0
	v_mov_b32_e32 v115, v0
	v_mov_b32_e32 v116, v0
	v_mov_b32_e32 v117, v0
	v_mov_b32_e32 v118, v0
	v_mov_b32_e32 v119, v0
	v_mov_b32_e32 v120, v0
	v_mov_b32_e32 v121, v0
	v_mov_b32_e32 v122, v0
	v_mov_b32_e32 v123, v0
	v_mov_b32_e32 v124, v0
	v_mov_b32_e32 v125, v0
	v_mov_b32_e32 v126, v0
	v_mov_b32_e32 v127, v0
	.p2align	6

; template <class Epi, class Sched, bool ALIGN_EPI, bool SP2, int KC>
; __device__ __forceinline__ void gemm_phase(PG8_LAS unsigned char* lds, const Gemm g, const Sched& S, const Epi& E, const int tid) {
;     ...
;         const bool has_next = S.next(ui + 1, nxt);
;         const char* nA = has_next ? (const char*)g.A + (size_t)nxt.pm * tstep : cA; const char* nB = has_next ? (const char*)g.Bt + (size_t)nxt.pn * tstep : cB;
;         for (int t = 0; t < nt; t += 2) {
;             const bool last = (t == nt - 2);
;             const char* a1 = cA + (size_t)(t + 1) * kstep;
;             const char* a2 = last ? nA : cA + (size_t)(t + 2) * kstep; const char* b2 = last ? nB : cB + (size_t)(t + 2) * kstep;
;             const char* a3 = a2 + kstep; const char* b3 = b2 + kstep;
;     ...
;         for (int a = 0; a < 2; ++a)
; #pragma unroll
;             for (int b = 0; b < 2; ++b)
; #pragma unroll
;                 for (int m = 0; m < 4; ++m)
; #pragma unroll
;                     for (int n = 0; n < 2; ++n) acc[a][b][m][n] = (f32x4){0.f, 0.f, 0.f, 0.f};
.LBB0_161:
	s_ashr_i32 s41, s40, 31
	s_lshl_b64 s[18:19], s[40:41], 19
	v_readlane_b32 s39, v254, 54
	s_add_u32 s42, s39, s18
	v_readlane_b32 s18, v254, 55
	s_addc_u32 s43, s18, s19
	s_and_b64 s[18:19], s[14:15], exec
	s_cselect_b32 s41, s43, s5
	s_cselect_b32 s47, s42, s4
	s_ashr_i32 s39, s38, 31
	s_lshl_b64 s[18:19], s[38:39], 19
	v_readlane_b32 s39, v254, 50
	s_add_u32 s44, s39, s18
	v_readlane_b32 s18, v254, 51
	s_addc_u32 s45, s18, s19
	s_and_b64 s[18:19], s[14:15], exec
	s_cselect_b32 s39, s45, s17
	s_cselect_b32 s49, s44, s16
	s_add_u32 s4, s4, 0x40080
	s_addc_u32 s5, s5, 0
	s_add_u32 s64, s16, 0x100
	v_mov_b32_e32 v0, 0
	s_addc_u32 s65, s17, 0
	s_mov_b32 s70, -2
	s_waitcnt lgkmcnt(0)
	v_mov_b32_e32 v1, v0
	v_mov_b32_e32 v2, v0
	v_mov_b32_e32 v3, v0
	v_mov_b32_e32 v16, v0
	v_mov_b32_e32 v17, v0
	v_mov_b32_e32 v18, v0
	v_mov_b32_e32 v19, v0
	v_mov_b32_e32 v4, v0
	v_mov_b32_e32 v5, v0
	v_mov_b32_e32 v6, v0
	v_mov_b32_e32 v7, v0
	v_mov_b32_e32 v20, v0
	v_mov_b32_e32 v21, v0
	v_mov_b32_e32 v22, v0
	v_mov_b32_e32 v23, v0
	v_mov_b32_e32 v8, v0
	v_mov_b32_e32 v9, v0
	v_mov_b32_e32 v10, v0
	v_mov_b32_e32 v11, v0
	v_mov_b32_e32 v24, v0
	v_mov_b32_e32 v25, v0
	v_mov_b32_e32 v26, v0
	v_mov_b32_e32 v27, v0
	v_mov_b32_e32 v12, v0
	v_mov_b32_e32 v13, v0
	v_mov_b32_e32 v14, v0
	v_mov_b32_e32 v15, v0
	v_mov_b32_e32 v28, v0
	v_mov_b32_e32 v29, v0
	v_mov_b32_e32 v30, v0
	v_mov_b32_e32 v31, v0
	v_mov_b32_e32 v32, v0
	v_mov_b32_e32 v33, v0
	v_mov_b32_e32 v34, v0
	v_mov_b32_e32 v35, v0
	v_mov_b32_e32 v48, v0
	v_mov_b32_e32 v49, v0
	v_mov_b32_e32 v50, v0
	v_mov_b32_e32 v51, v0
	v_mov_b32_e32 v36, v0
	v_mov_b32_e32 v37, v0
	v_mov_b32_e32 v38, v0
	v_mov_b32_e32 v39, v0
	v_mov_b32_e32 v52, v0
	v_mov_b32_e32 v53, v0
	v_mov_b32_e32 v54, v0
	v_mov_b32_e32 v55, v0
	v_mov_b32_e32 v40, v0
	v_mov_b32_e32 v41, v0
	v_mov_b32_e32 v42, v0
	v_mov_b32_e32 v43, v0
	v_mov_b32_e32 v56, v0
	v_mov_b32_e32 v57, v0
	v_mov_b32_e32 v58, v0
	v_mov_b32_e32 v59, v0
	v_mov_b32_e32 v44, v0
	v_mov_b32_e32 v45, v0
	v_mov_b32_e32 v46, v0
	v_mov_b32_e32 v47, v0
	v_mov_b32_e32 v60, v0
	v_mov_b32_e32 v61, v0
	v_mov_b32_e32 v62, v0
	v_mov_b32_e32 v63, v0
	v_mov_b32_e32 v64, v0
	v_mov_b32_e32 v65, v0
	v_mov_b32_e32 v66, v0
	v_mov_b32_e32 v67, v0
	v_mov_b32_e32 v80, v0
	v_mov_b32_e32 v81, v0
	v_mov_b32_e32 v82, v0
	v_mov_b32_e32 v83, v0
	v_mov_b32_e32 v68, v0
	v_mov_b32_e32 v69, v0
	v_mov_b32_e32 v70, v0
	v_mov_b32_e32 v71, v0
	v_mov_b32_e32 v84, v0
	v_mov_b32_e32 v85, v0
	v_mov_b32_e32 v86, v0
	v_mov_b32_e32 v87, v0
	v_mov_b32_e32 v72, v0
	v_mov_b32_e32 v73, v0
	v_mov_b32_e32 v74, v0
	v_mov_b32_e32 v75, v0
	v_mov_b32_e32 v88, v0
	v_mov_b32_e32 v89, v0
	v_mov_b32_e32 v90, v0
	v_mov_b32_e32 v91, v0
	v_mov_b32_e32 v76, v0
	v_mov_b32_e32 v77, v0
	v_mov_b32_e32 v78, v0
	v_mov_b32_e32 v79, v0
	v_mov_b32_e32 v92, v0
	v_mov_b32_e32 v93, v0
	v_mov_b32_e32 v94, v0
	v_mov_b32_e32 v95, v0
	v_mov_b32_e32 v96, v0
	v_mov_b32_e32 v97, v0
	v_mov_b32_e32 v98, v0
	v_mov_b32_e32 v99, v0
	v_mov_b32_e32 v112, v0
	v_mov_b32_e32 v113, v0
	v_mov_b32_e32 v114, v0
	v_mov_b32_e32 v115, v0
	v_mov_b32_e32 v100, v0
	v_mov_b32_e32 v101, v0
	v_mov_b32_e32 v102, v0
	v_mov_b32_e32 v103, v0
	v_mov_b32_e32 v116, v0
	v_mov_b32_e32 v117, v0
	v_mov_b32_e32 v118, v0
	v_mov_b32_e32 v119, v0
	v_mov_b32_e32 v104, v0
	v_mov_b32_e32 v105, v0
	v_mov_b32_e32 v106, v0
	v_mov_b32_e32 v107, v0
	v_mov_b32_e32 v120, v0
	v_mov_b32_e32 v121, v0
	v_mov_b32_e32 v122, v0
	v_mov_b32_e32 v123, v0
	v_mov_b32_e32 v108, v0
	v_mov_b32_e32 v109, v0
	v_mov_b32_e32 v110, v0
	v_mov_b32_e32 v111, v0
	v_mov_b32_e32 v124, v0
	v_mov_b32_e32 v125, v0
	v_mov_b32_e32 v126, v0
	v_mov_b32_e32 v127, v0
	.p2align	6

; template <class Epi, class Sched, bool ALIGN_EPI, bool SP2, int KC>
; __device__ __forceinline__ void gemm_phase(PG8_LAS unsigned char* lds, const Gemm g, const Sched& S, const Epi& E, const int tid) {
;     ...
;         for (int t = 0; t < nt; t += 2) {
;             const bool last = (t == nt - 2);
;             const char* a1 = cA + (size_t)(t + 1) * kstep;
;             const char* a2 = last ? nA : cA + (size_t)(t + 2) * kstep; const char* b2 = last ? nB : cB + (size_t)(t + 2) * kstep;
;             const char* a3 = a2 + kstep; const char* b3 = b2 + kstep;
;     ...
;         for (int a = 0; a < 2; ++a)
; #pragma unroll
;             for (int b = 0; b < 2; ++b)
; #pragma unroll
;                 for (int m = 0; m < 4; ++m)
; #pragma unroll
;                     for (int n = 0; n < 2; ++n) acc[a][b][m][n] = (f32x4){0.f, 0.f, 0.f, 0.f};
.LBB0_559:
	s_add_u32 s31, s36, 0x100
	v_mov_b32_e32 v0, 0
	s_addc_u32 s35, s37, 0
	s_mov_b32 s48, -2
	s_waitcnt lgkmcnt(0)
	v_mov_b32_e32 v1, v0
	v_mov_b32_e32 v2, v0
	v_mov_b32_e32 v3, v0
	v_mov_b32_e32 v16, v0
	v_mov_b32_e32 v17, v0
	v_mov_b32_e32 v18, v0
	v_mov_b32_e32 v19, v0
	v_mov_b32_e32 v4, v0
	v_mov_b32_e32 v5, v0
	v_mov_b32_e32 v6, v0
	v_mov_b32_e32 v7, v0
	v_mov_b32_e32 v20, v0
	v_mov_b32_e32 v21, v0
	v_mov_b32_e32 v22, v0
	v_mov_b32_e32 v23, v0
	v_mov_b32_e32 v8, v0
	v_mov_b32_e32 v9, v0
	v_mov_b32_e32 v10, v0
	v_mov_b32_e32 v11, v0
	v_mov_b32_e32 v24, v0
	v_mov_b32_e32 v25, v0
	v_mov_b32_e32 v26, v0
	v_mov_b32_e32 v27, v0
	v_mov_b32_e32 v12, v0
	v_mov_b32_e32 v13, v0
	v_mov_b32_e32 v14, v0
	v_mov_b32_e32 v15, v0
	v_mov_b32_e32 v28, v0
	v_mov_b32_e32 v29, v0
	v_mov_b32_e32 v30, v0
	v_mov_b32_e32 v31, v0
	v_mov_b32_e32 v32, v0
	v_mov_b32_e32 v33, v0
	v_mov_b32_e32 v34, v0
	v_mov_b32_e32 v35, v0
	v_mov_b32_e32 v64, v0
	v_mov_b32_e32 v65, v0
	v_mov_b32_e32 v66, v0
	v_mov_b32_e32 v67, v0
	v_mov_b32_e32 v36, v0
	v_mov_b32_e32 v37, v0
	v_mov_b32_e32 v38, v0
	v_mov_b32_e32 v39, v0
	v_mov_b32_e32 v68, v0
	v_mov_b32_e32 v69, v0
	v_mov_b32_e32 v70, v0
	v_mov_b32_e32 v71, v0
	v_mov_b32_e32 v44, v0
	v_mov_b32_e32 v45, v0
	v_mov_b32_e32 v46, v0
	v_mov_b32_e32 v47, v0
	v_mov_b32_e32 v76, v0
	v_mov_b32_e32 v77, v0
	v_mov_b32_e32 v78, v0
	v_mov_b32_e32 v79, v0
	v_mov_b32_e32 v52, v0
	v_mov_b32_e32 v53, v0
	v_mov_b32_e32 v54, v0
	v_mov_b32_e32 v55, v0
	v_mov_b32_e32 v88, v0
	v_mov_b32_e32 v89, v0
	v_mov_b32_e32 v90, v0
	v_mov_b32_e32 v91, v0
	v_mov_b32_e32 v96, v0
	v_mov_b32_e32 v97, v0
	v_mov_b32_e32 v98, v0
	v_mov_b32_e32 v99, v0
	v_mov_b32_e32 v100, v0
	v_mov_b32_e32 v101, v0
	v_mov_b32_e32 v102, v0
	v_mov_b32_e32 v103, v0
	v_mov_b32_e32 v104, v0
	v_mov_b32_e32 v105, v0
	v_mov_b32_e32 v106, v0
	v_mov_b32_e32 v107, v0
	v_mov_b32_e32 v108, v0
	v_mov_b32_e32 v109, v0
	v_mov_b32_e32 v110, v0
	v_mov_b32_e32 v111, v0
	v_mov_b32_e32 v116, v0
	v_mov_b32_e32 v117, v0
	v_mov_b32_e32 v118, v0
	v_mov_b32_e32 v119, v0
	v_mov_b32_e32 v112, v0
	v_mov_b32_e32 v113, v0
	v_mov_b32_e32 v114, v0
	v_mov_b32_e32 v115, v0
	v_mov_b32_e32 v124, v0
	v_mov_b32_e32 v125, v0
	v_mov_b32_e32 v126, v0
	v_mov_b32_e32 v127, v0
	v_mov_b32_e32 v120, v0
	v_mov_b32_e32 v121, v0
	v_mov_b32_e32 v122, v0
	v_mov_b32_e32 v123, v0
	v_mov_b32_e32 v72, v0
	v_mov_b32_e32 v73, v0
	v_mov_b32_e32 v74, v0
	v_mov_b32_e32 v75, v0
	v_mov_b32_e32 v40, v0
	v_mov_b32_e32 v41, v0
	v_mov_b32_e32 v42, v0
	v_mov_b32_e32 v43, v0
	v_mov_b32_e32 v80, v0
	v_mov_b32_e32 v81, v0
	v_mov_b32_e32 v82, v0
	v_mov_b32_e32 v83, v0
	v_mov_b32_e32 v48, v0
	v_mov_b32_e32 v49, v0
	v_mov_b32_e32 v50, v0
	v_mov_b32_e32 v51, v0
	v_mov_b32_e32 v84, v0
	v_mov_b32_e32 v85, v0
	v_mov_b32_e32 v86, v0
	v_mov_b32_e32 v87, v0
	v_mov_b32_e32 v56, v0
	v_mov_b32_e32 v57, v0
	v_mov_b32_e32 v58, v0
	v_mov_b32_e32 v59, v0
	v_mov_b32_e32 v92, v0
	v_mov_b32_e32 v93, v0
	v_mov_b32_e32 v94, v0
	v_mov_b32_e32 v95, v0
	v_mov_b32_e32 v60, v0
	v_mov_b32_e32 v61, v0
	v_mov_b32_e32 v62, v0
	v_mov_b32_e32 v63, v0
	.p2align	6

; template <class Epi, class Sched, bool ALIGN_EPI, bool SP2, int KC>
; __device__ __forceinline__ void gemm_phase(PG8_LAS unsigned char* lds, const Gemm g, const Sched& S, const Epi& E, const int tid) {
;     ...
;         const bool has_next = S.next(ui + 1, nxt);
;         const char* nA = has_next ? (const char*)g.A + (size_t)nxt.pm * tstep : cA; const char* nB = has_next ? (const char*)g.Bt + (size_t)nxt.pn * tstep : cB;
;         for (int t = 0; t < nt; t += 2) {
;             const bool last = (t == nt - 2);
;             const char* a1 = cA + (size_t)(t + 1) * kstep;
;             const char* a2 = last ? nA : cA + (size_t)(t + 2) * kstep; const char* b2 = last ? nB : cB + (size_t)(t + 2) * kstep;
;             const char* a3 = a2 + kstep; const char* b3 = b2 + kstep;
;     ...
;         for (int a = 0; a < 2; ++a)
; #pragma unroll
;             for (int b = 0; b < 2; ++b)
; #pragma unroll
;                 for (int m = 0; m < 4; ++m)
; #pragma unroll
;                     for (int n = 0; n < 2; ++n) acc[a][b][m][n] = (f32x4){0.f, 0.f, 0.f, 0.f};
.LBB0_729:
	s_ashr_i32 s17, s16, 31
	s_lshl_b64 s[18:19], s[16:17], 19
	s_add_u32 s18, s68, s18
	s_addc_u32 s19, s69, s19
	s_and_b64 s[20:21], s[8:9], exec
	s_cselect_b32 s17, s19, s5
	s_cselect_b32 s36, s18, s4
	s_ashr_i32 s15, s14, 31
	s_lshl_b64 s[20:21], s[14:15], 19
	v_readlane_b32 s15, v254, 36
	s_add_u32 s20, s15, s20
	v_readlane_b32 s15, v254, 37
	s_addc_u32 s21, s15, s21
	s_and_b64 s[24:25], s[8:9], exec
	s_cselect_b32 s15, s21, s23
	s_cselect_b32 s37, s20, s22
	s_add_u32 s4, s4, 0x40080
	s_addc_u32 s5, s5, 0
	s_add_u32 s38, s22, 0x100
	v_mov_b32_e32 v0, 0
	s_addc_u32 s39, s23, 0
	s_mov_b32 s40, -2
	v_mov_b32_e32 v1, v0
	v_mov_b32_e32 v2, v0
	v_mov_b32_e32 v3, v0
	v_mov_b32_e32 v4, v0
	v_mov_b32_e32 v5, v0
	v_mov_b32_e32 v6, v0
	v_mov_b32_e32 v7, v0
	v_mov_b32_e32 v8, v0
	v_mov_b32_e32 v9, v0
	v_mov_b32_e32 v10, v0
	v_mov_b32_e32 v11, v0
	v_mov_b32_e32 v12, v0
	v_mov_b32_e32 v13, v0
	v_mov_b32_e32 v14, v0
	v_mov_b32_e32 v15, v0
	v_mov_b32_e32 v16, v0
	v_mov_b32_e32 v17, v0
	v_mov_b32_e32 v18, v0
	v_mov_b32_e32 v19, v0
	v_mov_b32_e32 v20, v0
	v_mov_b32_e32 v21, v0
	v_mov_b32_e32 v22, v0
	v_mov_b32_e32 v23, v0
	v_mov_b32_e32 v24, v0
	v_mov_b32_e32 v25, v0
	v_mov_b32_e32 v26, v0
	v_mov_b32_e32 v27, v0
	v_mov_b32_e32 v28, v0
	v_mov_b32_e32 v29, v0
	v_mov_b32_e32 v30, v0
	v_mov_b32_e32 v31, v0
	v_mov_b32_e32 v60, v0
	v_mov_b32_e32 v61, v0
	v_mov_b32_e32 v62, v0
	v_mov_b32_e32 v63, v0
	v_mov_b32_e32 v64, v0
	v_mov_b32_e32 v65, v0
	v_mov_b32_e32 v66, v0
	v_mov_b32_e32 v67, v0
	v_mov_b32_e32 v72, v0
	v_mov_b32_e32 v73, v0
	v_mov_b32_e32 v74, v0
	v_mov_b32_e32 v75, v0
	v_mov_b32_e32 v76, v0
	v_mov_b32_e32 v77, v0
	v_mov_b32_e32 v78, v0
	v_mov_b32_e32 v79, v0
	v_mov_b32_e32 v80, v0
	v_mov_b32_e32 v81, v0
	v_mov_b32_e32 v82, v0
	v_mov_b32_e32 v83, v0
	v_mov_b32_e32 v84, v0
	v_mov_b32_e32 v85, v0
	v_mov_b32_e32 v86, v0
	v_mov_b32_e32 v87, v0
	v_mov_b32_e32 v88, v0
	v_mov_b32_e32 v89, v0
	v_mov_b32_e32 v90, v0
	v_mov_b32_e32 v91, v0
	v_mov_b32_e32 v92, v0
	v_mov_b32_e32 v93, v0
	v_mov_b32_e32 v94, v0
	v_mov_b32_e32 v95, v0
	v_mov_b32_e32 v32, v0
	v_mov_b32_e32 v33, v0
	v_mov_b32_e32 v34, v0
	v_mov_b32_e32 v35, v0
	v_mov_b32_e32 v36, v0
	v_mov_b32_e32 v37, v0
	v_mov_b32_e32 v38, v0
	v_mov_b32_e32 v39, v0
	v_mov_b32_e32 v40, v0
	v_mov_b32_e32 v41, v0
	v_mov_b32_e32 v42, v0
	v_mov_b32_e32 v43, v0
	v_mov_b32_e32 v44, v0
	v_mov_b32_e32 v45, v0
	v_mov_b32_e32 v46, v0
	v_mov_b32_e32 v47, v0
	v_mov_b32_e32 v48, v0
	v_mov_b32_e32 v49, v0
	v_mov_b32_e32 v50, v0
	v_mov_b32_e32 v51, v0
	v_mov_b32_e32 v52, v0
	v_mov_b32_e32 v53, v0
	v_mov_b32_e32 v54, v0
	v_mov_b32_e32 v55, v0
	v_mov_b32_e32 v56, v0
	v_mov_b32_e32 v57, v0
	v_mov_b32_e32 v58, v0
	v_mov_b32_e32 v59, v0
	v_mov_b32_e32 v68, v0
	v_mov_b32_e32 v69, v0
	v_mov_b32_e32 v70, v0
	v_mov_b32_e32 v71, v0
	v_mov_b32_e32 v96, v0
	v_mov_b32_e32 v97, v0
	v_mov_b32_e32 v98, v0
	v_mov_b32_e32 v99, v0
	v_mov_b32_e32 v100, v0
	v_mov_b32_e32 v101, v0
	v_mov_b32_e32 v102, v0
	v_mov_b32_e32 v103, v0
	v_mov_b32_e32 v104, v0
	v_mov_b32_e32 v105, v0
	v_mov_b32_e32 v106, v0
	v_mov_b32_e32 v107, v0
	v_mov_b32_e32 v108, v0
	v_mov_b32_e32 v109, v0
	v_mov_b32_e32 v110, v0
	v_mov_b32_e32 v111, v0
	v_mov_b32_e32 v112, v0
	v_mov_b32_e32 v113, v0
	v_mov_b32_e32 v114, v0
	v_mov_b32_e32 v115, v0
	v_mov_b32_e32 v116, v0
	v_mov_b32_e32 v117, v0
	v_mov_b32_e32 v118, v0
	v_mov_b32_e32 v119, v0
	v_mov_b32_e32 v120, v0
	v_mov_b32_e32 v121, v0
	v_mov_b32_e32 v122, v0
	v_mov_b32_e32 v123, v0
	v_mov_b32_e32 v124, v0
	v_mov_b32_e32 v125, v0
	v_mov_b32_e32 v126, v0
	v_mov_b32_e32 v127, v0
	.p2align	6
